# plus one static priority raise for waves 4-7 through the diff-attention unit loop
# speedup vs baseline: 1.0026x; 1.0026x over previous
; template <int PHM, int PH> __device__ __forceinline__ void run_phase(const Args& a, LAS unsigned char* lds0, int dry) {
;     ...
;     const int G = (int)gridDim.x + z_, bx = (int)blockIdx.x + z_;
;     const int vcu = (G % 8 == 0) ? (bx % 8) * (G / 8) + bx / 8 : bx;
.LBB0_615:
	s_cmp_lt_i32 s20, 7
	s_cselect_b64 s[0:1], -1, 0
	s_cmp_gt_i32 s21, 6
	s_cselect_b64 s[2:3], -1, 0
	s_and_b64 s[0:1], s[0:1], s[2:3]
	s_andn2_b64 vcc, exec, s[0:1]
	s_cbranch_vccnz .LBB0_750
	v_readfirstlane_b32 s100, v198
	s_nop 3
	s_lshr_b32 s100, s100, 8
	s_cmp_eq_u32 s100, 0
	s_cbranch_scc1 .Lprio_skip_6
	s_setprio 1
.Lprio_skip_6:
	v_mov_b32_e32 v176, v198
	s_mov_b32 s1, 0
	s_load_dwordx2 s[2:3], s[78:79], 0xc8
	v_readlane_b32 s0, v238, 0
	s_add_i32 s69, s1, s0
	s_waitcnt lgkmcnt(0)
	s_add_i32 s68, s1, s2
	s_and_b32 s0, s68, 7
	s_cmp_lg_u32 s0, 0
	v_readfirstlane_b32 s0, v176
	s_cbranch_scc1 .LBB0_618
	s_ashr_i32 s3, s69, 31
	s_lshr_b32 s3, s3, 29
	s_add_i32 s3, s69, s3
	s_ashr_i32 s4, s3, 3
	s_and_b32 s3, s3, -8
	s_ashr_i32 s2, s68, 3
	s_sub_i32 s3, s69, s3
	s_mul_i32 s2, s2, s3
	s_add_i32 s69, s2, s4

; #define LAS __attribute__((address_space(3)))
; __device__ __forceinline__ void r2_unit(const Args& a, unsigned char* ws, bf16* STB, LAS unsigned char* lds, int l, int unit, int tid, int wid, int lane, int dry) {
;     ...
;     const int n = unit & 15, h = (unit >> 4) & 3, b = unit >> 6;
;     float lgf2, lgb2; ret_gammas(a, l, h, lgf2, lgb2);
;     bf16* P = (bf16*)(ws + WS_P);
;     const bf16* kp = P + (size_t)(b * SEQ + n * 128) * NIN + 512 + h * 128;
;     const bf16* sp = STB + ((size_t)((b * 4 + h) * 16 + n) * 2) * 16384;
;     LAS unsigned char* KT = lds, * VT = lds + 32768, * SF = lds + 65536, * SB = lds + 98304;
; #pragma unroll
;     for (int i = 0; i < 4; ++i) {
;         const int c = tid + 512 * i, row = c >> 4, ch = c & 15; const unsigned o = offb(row, ch);
;         const u32x4 kv = *(const u32x4*)(kp + (size_t)row * NIN + ch * 8), vv = *(const u32x4*)(kp + 512 + (size_t)row * NIN + ch * 8);
;         const u32x4 sf = *(const u32x4*)(sp + row * 128 + ch * 8), sb = *(const u32x4*)(sp + 16384 + row * 128 + ch * 8);
;         *(LAS u32x4*)(KT + o) = kv; *(LAS u32x4*)(VT + o) = vv; *(LAS u32x4*)(SF + o) = sf; *(LAS u32x4*)(SB + o) = sb;
;     }
;     const int r32 = lane & 31, hi = lane >> 5, g1 = (lane >> 4) & 1, q4 = (lane & 15) >> 2, p4 = lane & 3;
;     const int cb = wid & 3, eh = wid >> 2;
;     const int cl = 32 * cb + r32;
;     const size_t tok = (size_t)b * SEQ + n * 128 + cl;
;     bf16x8 qf[8];
; #pragma unroll
;     for (int kd = 0; kd < 8; ++kd) qf[kd] = *(const bf16x8*)(P + tok * NIN + h * 128 + 16 * kd + 8 * hi);
;     __syncthreads();
;     f32x16 O[2], XF[2], XB[2];
; #pragma unroll
;     for (int e = 0; e < 2; ++e)
; #pragma unroll
;         for (int r = 0; r < 16; ++r) { O[e][r] = 0.f; XF[e][r] = 0.f; XB[e][r] = 0.f; }
;     float ff[16], fb[16];
; #pragma unroll
;     for (int r = 0; r < 16; ++r) { ff[r] = __builtin_amdgcn_exp2f((float)(31 - crow(r, hi)) * lgf2); fb[r] = __builtin_amdgcn_exp2f((float)crow(r, hi) * lgb2); }
;     unsigned vp[2][2], sn[2][2], kb[8];
; #pragma unroll
;     for (int e = 0; e < 2; ++e)
; #pragma unroll
;         for (int tt = 0; tt < 2; ++tt) { vp[e][tt] = tr_base_perm(2 * eh + e, tt, lane); sn[e][tt] = tr_base_nat(2 * eh + e, tt, lane); }
; #pragma unroll
;     for (int kd = 0; kd < 8; ++kd) kb[kd] = row_base(2 * kd, lane);
.LBB0_662:
	s_setprio 0
	v_writelane_b32 v238, s76, 9
	s_add_u32 s1, s16, s1
	s_addc_u32 s45, s17, s28
	v_writelane_b32 v238, s77, 10
	s_ashr_i32 s2, s0, 8
	v_writelane_b32 v238, s1, 11
	s_bfe_u32 s1, s0, 0x20006
	s_lshl_b32 s38, s2, 1
	s_add_i32 s67, s70, 0x10000
	s_add_i32 s46, s70, 0x18000
	s_lshl_b32 s33, s1, 5
	s_or_b32 s39, s38, 1
	s_cmp_lg_u32 s1, 0
	s_cselect_b64 s[54:55], -1, 0
	s_cmp_lt_u32 s1, 2
	s_cselect_b64 s[56:57], -1, 0
	s_cmp_lg_u32 s1, 3
	s_cselect_b64 s[58:59], -1, 0
	s_cmp_gt_u32 s1, 1
	s_cselect_b64 s[0:1], -1, 0
	v_writelane_b32 v238, s0, 12
	s_lshl_b32 s3, s2, 10
	s_add_i32 s3, s71, s3
	v_writelane_b32 v238, s1, 13
	v_writelane_b32 v238, s3, 14
	s_lshl_b32 s97, s2, 7
	s_lshl_b32 s62, s2, 6
	v_readlane_b32 s2, v238, 7
	v_readlane_b32 s3, v238, 8
	s_load_dwordx4 s[40:43], s[2:3], 0x40
	s_add_i32 s0, s70, 0x10400
	s_add_i32 s1, s70, 0x18400
	s_add_i32 s47, s70, 0x11000
	s_add_i32 s48, s70, 0x11400
	s_add_i32 s49, s70, 0x19000
	s_add_i32 s66, s70, 0x19400
	s_add_i32 s72, s70, 0x12000
	s_add_i32 s73, s70, 0x12400
	s_add_i32 s74, s70, 0x1a000
	s_add_i32 s75, s70, 0x1a400
	s_add_i32 s76, s70, 0x13000
	s_add_i32 s77, s70, 0x13400
	s_add_i32 s78, s70, 0x1b000
	s_add_i32 s79, s70, 0x1b400
	s_add_i32 s80, s70, 0x14000
	s_add_i32 s81, s70, 0x14400
	s_add_i32 s82, s70, 0x1c000
	s_add_i32 s83, s70, 0x1c400
	s_add_i32 s84, s70, 0x15000
	s_add_i32 s85, s70, 0x15400
	s_add_i32 s86, s70, 0x1d000
	s_add_i32 s87, s70, 0x1d400
	s_add_i32 s88, s70, 0x16000
	s_add_i32 s89, s70, 0x16400
	s_add_i32 s90, s70, 0x1e000
	s_add_i32 s91, s70, 0x1e400
	s_add_i32 s92, s70, 0x17000
	s_add_i32 s93, s70, 0x17400
	s_add_i32 s94, s70, 0x1f000
	s_add_i32 s95, s70, 0x1f400
	s_cmp_eq_u32 s30, 0
	s_mov_b32 s53, 0
	s_cselect_b64 s[64:65], -1, 0
	s_ashr_i32 s63, s62, 31
	v_mov_b32_e32 v125, 0
	v_mov_b32_e32 v134, 0x7f800000
	v_mov_b32_e32 v135, 0x3ecc95a3
	s_mov_b32 s96, 0x3f317218
	s_mov_b32 s60, 0x33800000
	s_movk_i32 s61, 0x1c00
	v_mov_b64_e32 v[126:127], s[50:51]
	v_mov_b32_e32 v136, 0x1c00
	v_cndmask_b32_e64 v137, 0, 1, s[54:55]
	s_branch .LBB0_664

; template <int PHM, int PH> __device__ __forceinline__ void run_phase(const Args& a, LAS unsigned char* lds0, int dry) {
;     ...
;     const int G = (int)gridDim.x + z_, bx = (int)blockIdx.x + z_;
;     const int vcu = (G % 8 == 0) ? (bx % 8) * (G / 8) + bx / 8 : bx;
.LBB0_1343:
	s_cmp_lt_i32 s20, 17
	s_cselect_b64 s[0:1], -1, 0
	s_cmp_gt_i32 s21, 16
	s_cselect_b64 s[2:3], -1, 0
	s_and_b64 s[0:1], s[0:1], s[2:3]
	s_andn2_b64 vcc, exec, s[0:1]
	s_cbranch_vccnz .LBB0_1478
	v_readfirstlane_b32 s100, v198
	s_nop 3
	s_lshr_b32 s100, s100, 8
	s_cmp_eq_u32 s100, 0
	s_cbranch_scc1 .Lprio_skip_16
	s_setprio 1

; #define LAS __attribute__((address_space(3)))
; __device__ __forceinline__ void r2_unit(const Args& a, unsigned char* ws, bf16* STB, LAS unsigned char* lds, int l, int unit, int tid, int wid, int lane, int dry) {
;     ...
;     const int n = unit & 15, h = (unit >> 4) & 3, b = unit >> 6;
;     float lgf2, lgb2; ret_gammas(a, l, h, lgf2, lgb2);
;     bf16* P = (bf16*)(ws + WS_P);
;     const bf16* kp = P + (size_t)(b * SEQ + n * 128) * NIN + 512 + h * 128;
;     const bf16* sp = STB + ((size_t)((b * 4 + h) * 16 + n) * 2) * 16384;
;     LAS unsigned char* KT = lds, * VT = lds + 32768, * SF = lds + 65536, * SB = lds + 98304;
; #pragma unroll
;     for (int i = 0; i < 4; ++i) {
;         const int c = tid + 512 * i, row = c >> 4, ch = c & 15; const unsigned o = offb(row, ch);
;         const u32x4 kv = *(const u32x4*)(kp + (size_t)row * NIN + ch * 8), vv = *(const u32x4*)(kp + 512 + (size_t)row * NIN + ch * 8);
;         const u32x4 sf = *(const u32x4*)(sp + row * 128 + ch * 8), sb = *(const u32x4*)(sp + 16384 + row * 128 + ch * 8);
;         *(LAS u32x4*)(KT + o) = kv; *(LAS u32x4*)(VT + o) = vv; *(LAS u32x4*)(SF + o) = sf; *(LAS u32x4*)(SB + o) = sb;
;     }
;     const int r32 = lane & 31, hi = lane >> 5, g1 = (lane >> 4) & 1, q4 = (lane & 15) >> 2, p4 = lane & 3;
;     const int cb = wid & 3, eh = wid >> 2;
;     const int cl = 32 * cb + r32;
;     const size_t tok = (size_t)b * SEQ + n * 128 + cl;
;     bf16x8 qf[8];
; #pragma unroll
;     for (int kd = 0; kd < 8; ++kd) qf[kd] = *(const bf16x8*)(P + tok * NIN + h * 128 + 16 * kd + 8 * hi);
;     __syncthreads();
;     f32x16 O[2], XF[2], XB[2];
; #pragma unroll
;     for (int e = 0; e < 2; ++e)
; #pragma unroll
;         for (int r = 0; r < 16; ++r) { O[e][r] = 0.f; XF[e][r] = 0.f; XB[e][r] = 0.f; }
;     float ff[16], fb[16];
; #pragma unroll
;     for (int r = 0; r < 16; ++r) { ff[r] = __builtin_amdgcn_exp2f((float)(31 - crow(r, hi)) * lgf2); fb[r] = __builtin_amdgcn_exp2f((float)crow(r, hi) * lgb2); }
;     unsigned vp[2][2], sn[2][2], kb[8];
; #pragma unroll
;     for (int e = 0; e < 2; ++e)
; #pragma unroll
;         for (int tt = 0; tt < 2; ++tt) { vp[e][tt] = tr_base_perm(2 * eh + e, tt, lane); sn[e][tt] = tr_base_nat(2 * eh + e, tt, lane); }
; #pragma unroll
;     for (int kd = 0; kd < 8; ++kd) kb[kd] = row_base(2 * kd, lane);
.LBB0_1390:
	s_setprio 0
	v_writelane_b32 v238, s76, 9
	s_add_u32 s1, s16, s1
	s_addc_u32 s73, s17, s28
	v_writelane_b32 v238, s77, 10
	v_writelane_b32 v238, s1, 11
	s_bfe_u32 s1, s0, 0x20006
	s_ashr_i32 s0, s0, 8
	s_lshl_b32 s77, s0, 1
	s_add_i32 s74, s70, 0x10000
	s_add_i32 s75, s70, 0x18000
	s_lshl_b32 s76, s1, 5
	s_or_b32 s78, s77, 1
	s_cmp_lg_u32 s1, 0
	s_cselect_b64 s[54:55], -1, 0
	s_cmp_lt_u32 s1, 2
	s_cselect_b64 s[56:57], -1, 0
	s_cmp_lg_u32 s1, 3
	s_cselect_b64 s[58:59], -1, 0
	s_cmp_gt_u32 s1, 1
	s_cselect_b64 s[2:3], -1, 0
	v_writelane_b32 v238, s2, 12
	s_lshl_b32 s1, s0, 10
	s_add_i32 s1, s71, s1
	v_writelane_b32 v238, s3, 13
	v_writelane_b32 v238, s1, 14
	s_lshl_b32 s61, s0, 7
	s_lshl_b32 s62, s0, 6
	v_readlane_b32 s0, v238, 7
	v_readlane_b32 s1, v238, 8
	s_load_dwordx4 s[40:43], s[0:1], 0x40
	s_add_i32 s79, s70, 0x10400
	s_add_i32 s80, s70, 0x18400
	s_add_i32 s81, s70, 0x11000
	s_add_i32 s82, s70, 0x11400
	s_add_i32 s83, s70, 0x19000
	s_add_i32 s84, s70, 0x19400
	s_add_i32 s85, s70, 0x12000
	s_add_i32 s86, s70, 0x12400
	s_add_i32 s87, s70, 0x1a000
	s_add_i32 s88, s70, 0x1a400
	s_add_i32 s89, s70, 0x13000
	s_add_i32 s90, s70, 0x13400
	s_add_i32 s91, s70, 0x1b000
	s_add_i32 s92, s70, 0x1b400
	s_add_i32 s93, s70, 0x14000
	s_add_i32 s94, s70, 0x14400
	s_add_i32 s95, s70, 0x1c000
	s_add_i32 s96, s70, 0x1c400
	s_add_i32 s97, s70, 0x15000
	s_add_i32 s67, s70, 0x15400
	s_add_i32 s44, s70, 0x1d000
	s_add_i32 s45, s70, 0x1d400
	s_add_i32 s46, s70, 0x16000
	s_add_i32 s47, s70, 0x16400
	s_add_i32 s33, s70, 0x1e000
	s_add_i32 s66, s70, 0x1e400
	s_add_i32 s38, s70, 0x17000
	s_add_i32 s39, s70, 0x17400
	s_add_i32 s48, s70, 0x1f000
	s_add_i32 s49, s70, 0x1f400
	s_cmp_eq_u32 s30, 0
	s_mov_b32 s53, 0
	s_cselect_b64 s[64:65], -1, 0
	s_ashr_i32 s63, s62, 31
	v_mov_b32_e32 v125, 0
	v_mov_b32_e32 v134, 0x7f800000
	v_mov_b32_e32 v135, 0x3ecc95a3
	s_mov_b32 s60, 0x3f317218
	s_mov_b32 s0, 0x33800000
	s_movk_i32 s1, 0x1c00
	v_mov_b64_e32 v[126:127], s[50:51]
	v_mov_b32_e32 v136, 0x1c00
	v_cndmask_b32_e64 v137, 0, 1, s[54:55]
	s_branch .LBB0_1392
